# layer-1 weight conversion tiles 864..2399 moved from the prompt mixer phase into idle slots of the sample mixer phase (workgroups without an hgrn item)
# speedup vs baseline: 1.0068x; 1.0068x over previous
.LBB0_225:
	v_writelane_b32 v255, s12, 6
	s_andn2_b64 vcc, exec, s[4:5]
	s_nop 0
	v_writelane_b32 v255, s13, 7
	v_writelane_b32 v255, s0, 10
	s_nop 1
	v_writelane_b32 v255, s1, 11
	v_writelane_b32 v255, s77, 12
	s_cbranch_vccnz .LBB0_308
	s_cmp_eq_u32 s6, 14
	s_cselect_b32 vcc_lo, 1, 0
	v_writelane_b32 v255, vcc_lo, 30
	s_add_i32 s20, s6, 18
	s_cmp_gt_u32 s20, 38
	s_cselect_b64 s[0:1], -1, 0
	s_lshl_b32 s4, s74, 2
	v_writelane_b32 v255, s0, 4
	s_ashr_i32 s5, s4, 31
	s_lshl_b64 s[4:5], s[4:5], 2
	v_writelane_b32 v255, s1, 5
	v_readlane_b32 s0, v252, 24
	s_add_u32 s4, s0, s4
	v_readlane_b32 s0, v252, 25
	s_addc_u32 s5, s0, s5
	v_writelane_b32 v255, s4, 13
	s_cmp_lt_u32 s20, 39
	s_mov_b32 s0, 0x4c25000
	v_writelane_b32 v255, s5, 14
	s_movk_i32 s4, 0x960
	v_readlane_b32 s16, v255, 6
	v_readlane_b32 s17, v255, 7
	s_cselect_b32 s34, s4, 0x600
	s_and_b64 s[4:5], s[16:17], exec
	v_readlane_b32 s36, v252, 4
	s_cselect_b32 s4, s0, 0x9c25000
	v_readlane_b32 s50, v252, 18
	v_readlane_b32 s51, v252, 19
	s_add_u32 s0, s50, s4
	s_addc_u32 s1, s51, 0
	v_writelane_b32 v255, s0, 8
	s_and_b64 s[4:5], s[16:17], exec
	v_readlane_b32 s52, v253, 8
	v_writelane_b32 v255, s1, 9
	s_mov_b32 s0, 0xfd25000
	s_cselect_b32 s4, s0, 0x6425000
	s_add_u32 s0, s50, s4
	s_addc_u32 s1, s51, 0
	v_writelane_b32 v255, s0, 15
	v_readlane_b32 s66, v253, 22
	v_readlane_b32 s67, v253, 23
	v_writelane_b32 v255, s1, 16
	v_readlane_b32 s24, v252, 34
	v_readlane_b32 s0, v255, 2
	s_lshl_b32 s4, s0, 7
	s_ashr_i32 s5, s4, 31
	s_lshl_b64 s[4:5], s[4:5], 2
	v_readlane_b32 s1, v255, 3
	s_mov_b32 s26, s0
	s_add_u32 s0, s66, s4
	s_addc_u32 s1, s67, s5
	v_writelane_b32 v255, s0, 17
	s_and_b64 s[20:21], s[16:17], exec
	s_cselect_b32 s35, 4, 64
	v_writelane_b32 v255, s1, 18
	s_movk_i32 s0, 0x100
	s_cselect_b32 s13, s0, 0x1100
	s_cselect_b32 s14, 8, 12
	s_ashr_i32 s27, s26, 31
	s_lshl_b32 s0, s13, 8
	s_lshl_b32 s15, s13, 7
	s_lshr_b32 s77, s13, 6
	s_lshl_b32 s22, s13, 6
	s_lshl_b64 s[20:21], s[26:27], 2
	v_writelane_b32 v255, s0, 19
	v_readlane_b32 s25, v252, 35
	s_add_u32 s0, s24, s20
	v_cvt_f32_ubyte0_e32 v0, s35
	s_addc_u32 s1, s25, s21
	v_rcp_iflag_f32_e32 v0, v0
	s_add_u32 s20, s50, s20
	v_writelane_b32 v255, s0, 20
	s_addc_u32 s21, s51, s21
	v_readlane_b32 s38, v252, 6
	v_writelane_b32 v255, s1, 21
	s_add_u32 s0, s20, 0x4b24008
	s_addc_u32 s1, s21, 0
	v_mul_f32_e32 v0, 0x4f7ffffe, v0
	v_readlane_b32 s39, v252, 7
	s_add_u32 s28, s38, s4
	v_cvt_u32_f32_e32 v0, v0
	s_addc_u32 s29, s39, s5
	s_and_b64 s[4:5], s[16:17], exec
	s_cselect_b32 s16, 1, 16
	v_readfirstlane_b32 s5, v0
	v_cvt_f32_ubyte0_e32 v0, s16
	v_rcp_iflag_f32_e32 v0, v0
	v_writelane_b32 v255, s0, 22
	s_sub_i32 s4, 0, s35
	s_mul_i32 s4, s4, s5
	v_mul_f32_e32 v0, 0x4f7ffffe, v0
	v_cvt_u32_f32_e32 v0, v0
	v_writelane_b32 v255, s1, 23
	s_mov_b32 s0, s26
	v_writelane_b32 v255, s0, 2
	s_mul_hi_u32 s4, s5, s4
	s_mov_b32 s75, 0x60000
	v_writelane_b32 v255, s1, 3
	s_add_i32 s0, s5, s4
	s_sub_i32 s4, 0, s16
	v_readfirstlane_b32 s5, v0
	s_mul_i32 s4, s4, s5
	s_mul_hi_u32 s4, s5, s4
	s_mov_b32 s76, 0x8000
	s_mov_b32 s23, s95
	s_lshl_b32 s17, s26, 1
	v_writelane_b32 v255, s0, 24
	s_add_i32 s0, s5, s4
	s_sub_i32 s12, 0, s77
	s_mov_b32 s96, s71
	v_readlane_b32 s37, v252, 5
	v_readlane_b32 s40, v252, 8
	v_readlane_b32 s41, v252, 9
	v_readlane_b32 s42, v252, 10
	v_readlane_b32 s43, v252, 11
	v_readlane_b32 s44, v252, 12
	v_readlane_b32 s45, v252, 13
	v_readlane_b32 s46, v252, 14
	v_readlane_b32 s47, v252, 15
	v_readlane_b32 s48, v252, 16
	v_readlane_b32 s49, v252, 17
	v_readlane_b32 s53, v253, 9
	v_readlane_b32 s54, v253, 10
	v_readlane_b32 s55, v253, 11
	v_readlane_b32 s56, v253, 12
	v_readlane_b32 s57, v253, 13
	v_readlane_b32 s58, v253, 14
	v_readlane_b32 s59, v253, 15
	v_readlane_b32 s60, v253, 16
	v_readlane_b32 s61, v253, 17
	v_readlane_b32 s62, v253, 18
	v_readlane_b32 s63, v253, 19
	v_readlane_b32 s64, v253, 20
	v_readlane_b32 s65, v253, 21
	s_branch .LBB0_229

.Lattn_static:
	s_waitcnt lgkmcnt(0)
	ds_read_b32 v2, v196 offset:4
	v_readlane_b32 s99, v255, 12
	s_waitcnt lgkmcnt(0)
	v_readfirstlane_b32 s24, v2
	s_nop 3
	s_and_b32 s25, s99, 7
	s_lshl_b32 s25, s25, 6
	s_lshr_b32 s26, s99, 3
	s_or_b32 s25, s25, s26
	s_add_i32 s25, s25, 0x100
	s_cmpk_lt_u32 s99, 0x100
	s_cselect_b32 s26, 0, 1
	s_add_i32 s26, s26, s24
	s_add_i32 s24, s24, 1
	s_cmp_eq_u32 s26, 1
	s_cselect_b32 s98, s25, 0x300
	s_cmp_eq_u32 s26, 0
	s_cselect_b32 s98, s99, s98
	v_readlane_b32 vcc_hi, v255, 30
	s_nop 3
	s_cmpk_lt_u32 s99, 0x100
	s_cbranch_scc1 .Lcv_no
	s_cmp_eq_u32 vcc_hi, 0
	s_cbranch_scc1 .Lcv_no
	s_cmp_lt_u32 s26, 2
	s_cbranch_scc1 .Lcv_no
	s_cmp_gt_u32 s26, 7
	s_cbranch_scc1 .Lcv_no
	s_sub_u32 vcc_lo, s26, 2
	s_lshl_b32 vcc_lo, vcc_lo, 8
	s_add_u32 s98, s99, vcc_lo
	s_add_u32 s98, s98, 0x660
	s_branch .Lcv_keep
.Lcv_no:
	s_cmp_gt_u32 s26, 1
	s_cselect_b32 s24, 0, s24
.Lcv_keep:
	v_mov_b32_e32 v2, s24
	ds_write_b32 v196, v2 offset:4
	v_mov_b32_e32 v2, s98

.LBB0_234:
	s_or_b64 exec, exec, s[4:5]
	s_waitcnt lgkmcnt(0)
	s_barrier
	ds_read_b32 v0, v196
	s_movk_i32 s1, 0x300
	s_waitcnt lgkmcnt(0)
	v_readfirstlane_b32 s25, v0
	s_add_i32 s26, s25, 0xffffff00
	s_cmpk_gt_i32 s25, 0xff
	s_cselect_b64 s[20:21], -1, 0
	v_cmp_gt_i32_e64 s[4:5], s1, v0
	v_cndmask_b32_e64 v0, 0, 1, s[20:21]
	s_and_b64 s[20:21], s[20:21], exec
	v_readfirstlane_b32 s24, v0
	s_cselect_b32 s25, s26, s25
	s_add_i32 s98, s26, 0x100
	s_cmpk_lt_u32 s98, 0x400
	s_cbranch_scc1 .Lk3_nc
	s_movk_i32 s24, 3
	s_sub_u32 s25, s98, 0x400
	s_mov_b64 s[4:5], exec
.Lk3_nc:
	s_branch .LBB0_237
.LBB0_235:
	s_mov_b64 s[4:5], 0
	s_cbranch_execz .LBB0_237
	s_add_i32 s20, s96, s81
	s_cmp_lt_i32 s96, s34
	s_cselect_b64 s[4:5], -1, 0
	s_cmpk_lt_i32 s96, 0x600
	s_movk_i32 s24, 0xfe00
	s_cselect_b32 s21, 2, 3
	s_cselect_b32 s25, s24, 0xfffffa00
	s_cmpk_lt_i32 s96, 0x200
	s_cselect_b32 s24, 1, s21
	s_cselect_b32 s21, 0, s25
	s_add_i32 s25, s21, s96
	s_mov_b32 s96, s20
